# remaining two hops (lane^16, lane^32) of the row-phase 64-lane sums via v_permlane16_swap / v_permlane32_swap (tmp = acc, swap, same add); the row phases no longer use ds_bpermute
# baseline (speedup 1.0000x reference)
; __device__ __forceinline__ unsigned cvt_pk_bf16(float lo, float hi) { unsigned r; asm volatile("v_cvt_pk_bf16_f32 %0, %1, %2" : "=v"(r) : "v"(lo), "v"(hi)); return r; }
; __device__ __forceinline__ float wave_sum(float v, int lane) {
; #pragma unroll
;     for (int o = 1; o < 64; o <<= 1) v += __uint_as_float((unsigned)__builtin_amdgcn_ds_bpermute((lane ^ o) << 2, (int)__float_as_uint(v)));
;     return v;
; }
; __device__ __forceinline__ void prep_row(const float* xrow, bf16_t* orow, float* ssq, float* rsb, int m, int lane) {
;     const f32x4* xr = (const f32x4*)xrow + lane; f32x4 v[8]; float s = 0.f;
; #pragma unroll
;     for (int j = 0; j < 8; ++j) { v[j] = xr[64 * j]; s += (v[j].x * v[j].x + v[j].y * v[j].y) + (v[j].z * v[j].z + v[j].w * v[j].w); }
;     const float tot = wave_sum(s, lane);
;     u32x2* o8 = (u32x2*)orow + lane;
; #pragma unroll
;     for (int j = 0; j < 8; ++j) { u32x2 w; w.x = cvt_pk_bf16(v[j].x, v[j].y); w.y = cvt_pk_bf16(v[j].z, v[j].w); o8[64 * j] = w; }
;     if (lane < 32) ssq[(size_t)lane * MTOK + m] = (lane == 0) ? tot : 0.f;
;     if (lane == 0) rsb[m] = rsqrtf(tot * (1.f / 2048.f) + EPS);
; }
.LBB0_184:
	global_load_dwordx4 v[16:19], v194, s[60:61]
	global_load_dwordx4 v[20:23], v194, s[60:61] offset:1024
	global_load_dwordx4 v[24:27], v194, s[60:61] offset:2048
	global_load_dwordx4 v[28:31], v194, s[60:61] offset:3072
	v_lshl_add_u64 v[32:33], s[60:61], 0, v[194:195]
	s_movk_i32 s49, 0x1000
	v_add_co_u32_e32 v44, vcc, s49, v32
	s_lshl_b64 s[60:61], s[58:59], 12
	s_nop 0
	v_addc_co_u32_e32 v45, vcc, 0, v33, vcc
	global_load_dwordx4 v[32:35], v[44:45], off
	global_load_dwordx4 v[36:39], v[44:45], off offset:1024
	global_load_dwordx4 v[40:43], v[44:45], off offset:2048
	s_nop 0
	global_load_dwordx4 v[44:47], v[44:45], off offset:3072
	s_waitcnt vmcnt(7)
	v_mul_f32_e32 v11, v17, v17
	v_mul_f32_e32 v13, v19, v19
	s_waitcnt vmcnt(6)
	v_mul_f32_e32 v14, v21, v21
	v_mul_f32_e32 v48, v23, v23
	s_waitcnt vmcnt(5)
	v_mul_f32_e32 v49, v25, v25
	v_mul_f32_e32 v50, v27, v27
	v_fmac_f32_e32 v11, v16, v16
	v_fmac_f32_e32 v13, v18, v18
	v_fmac_f32_e32 v14, v20, v20
	v_fmac_f32_e32 v48, v22, v22
	s_waitcnt vmcnt(4)
	v_mul_f32_e32 v51, v29, v29
	v_mul_f32_e32 v52, v31, v31
	v_fmac_f32_e32 v49, v24, v24
	v_fmac_f32_e32 v50, v26, v26
	v_add_f32_e32 v11, v11, v13
	v_add_f32_e32 v13, v14, v48
	v_fmac_f32_e32 v51, v28, v28
	v_fmac_f32_e32 v52, v30, v30
	v_add_f32_e32 v14, v49, v50
	s_waitcnt vmcnt(3)
	v_mul_f32_e32 v49, v33, v33
	v_mul_f32_e32 v50, v35, v35
	v_add_f32_e32 v11, v11, v13
	v_add_f32_e32 v48, v51, v52
	s_waitcnt vmcnt(2)
	v_mul_f32_e32 v51, v37, v37
	v_mul_f32_e32 v52, v39, v39
	v_fmac_f32_e32 v49, v32, v32
	v_fmac_f32_e32 v50, v34, v34
	v_add_f32_e32 v11, v11, v14
	s_waitcnt vmcnt(1)
	v_mul_f32_e32 v53, v41, v41
	v_mul_f32_e32 v54, v43, v43
	v_fmac_f32_e32 v51, v36, v36
	v_fmac_f32_e32 v52, v38, v38
	v_add_f32_e32 v13, v49, v50
	v_add_f32_e32 v11, v11, v48
	s_waitcnt vmcnt(0)
	v_mul_f32_e32 v55, v45, v45
	v_mul_f32_e32 v56, v47, v47
	v_fmac_f32_e32 v53, v40, v40
	v_fmac_f32_e32 v54, v42, v42
	v_add_f32_e32 v14, v51, v52
	v_add_f32_e32 v11, v11, v13
	v_fmac_f32_e32 v55, v44, v44
	v_fmac_f32_e32 v56, v46, v46
	v_add_f32_e32 v49, v53, v54
	v_add_f32_e32 v11, v11, v14
	v_add_f32_e32 v50, v55, v56
	v_add_f32_e32 v11, v11, v49
	v_add_f32_e32 v11, v11, v50
	s_nop 1
	v_mov_b32_dpp v13, v11 quad_perm:[1,0,3,2] row_mask:0xf bank_mask:0xf
	v_lshl_add_u64 v[48:49], v[0:1], 0, s[60:61]
	v_cvt_pk_bf16_f32 v16, v16, v17
	v_cvt_pk_bf16_f32 v17, v18, v19
	global_store_dwordx2 v[48:49], v[16:17], off
	s_waitcnt lgkmcnt(0)
	v_add_f32_e32 v11, v11, v13
	s_nop 1
	v_mov_b32_dpp v13, v11 quad_perm:[2,3,0,1] row_mask:0xf bank_mask:0xf
	v_cvt_pk_bf16_f32 v16, v20, v21
	v_cvt_pk_bf16_f32 v17, v22, v23
	global_store_dwordx2 v[48:49], v[16:17], off offset:512
	v_cvt_pk_bf16_f32 v16, v24, v25
	s_waitcnt lgkmcnt(0)
	v_add_f32_e32 v11, v11, v13
	s_nop 1
	v_mov_b32_dpp v13, v11 row_half_mirror row_mask:0xf bank_mask:0xf
	v_cvt_pk_bf16_f32 v17, v26, v27
	global_store_dwordx2 v[48:49], v[16:17], off offset:1024
	v_cvt_pk_bf16_f32 v16, v28, v29
	v_cvt_pk_bf16_f32 v17, v30, v31
	s_waitcnt lgkmcnt(0)
	v_add_f32_e32 v11, v11, v13
	s_nop 1
	v_mov_b32_dpp v13, v11 row_mirror row_mask:0xf bank_mask:0xf
	global_store_dwordx2 v[48:49], v[16:17], off offset:1536
	v_cvt_pk_bf16_f32 v16, v32, v33
	v_cvt_pk_bf16_f32 v17, v34, v35
	global_store_dwordx2 v[48:49], v[16:17], off offset:2048
	s_waitcnt lgkmcnt(0)
	v_add_f32_e32 v11, v11, v13
	v_mov_b32_e32 v13, v11
	s_nop 1
	v_permlane16_swap_b32_e32 v13, v11
	v_cvt_pk_bf16_f32 v16, v36, v37
	v_cvt_pk_bf16_f32 v17, v38, v39
	global_store_dwordx2 v[48:49], v[16:17], off offset:2560
	v_cvt_pk_bf16_f32 v16, v40, v41
	s_waitcnt lgkmcnt(0)
	v_add_f32_e32 v11, v11, v13
	v_mov_b32_e32 v13, v11
	s_nop 1
	v_permlane32_swap_b32_e32 v13, v11
	v_cvt_pk_bf16_f32 v17, v42, v43
	global_store_dwordx2 v[48:49], v[16:17], off offset:3072
	v_cvt_pk_bf16_f32 v16, v44, v45
	v_cvt_pk_bf16_f32 v17, v46, v47
	s_waitcnt lgkmcnt(0)
	v_add_f32_e32 v11, v11, v13
	global_store_dwordx2 v[48:49], v[16:17], off offset:3584
	s_and_saveexec_b64 s[60:61], s[36:37]
	s_cbranch_execz .LBB0_186
	v_cndmask_b32_e64 v13, 0, v11, s[38:39]
	v_lshl_add_u64 v[16:17], s[58:59], 2, v[2:3]
	global_store_dword v[16:17], v13, off

; __device__ __forceinline__ void norm_row(const float* xrow, const float* g, bf16_t* orow, float* copy, int lane) {
;     const f32x4* xr = (const f32x4*)xrow + lane; f32x4 v[8]; float s = 0.f;
; #pragma unroll
;     for (int j = 0; j < 8; ++j) { v[j] = xr[64 * j]; s += (v[j].x * v[j].x + v[j].y * v[j].y) + (v[j].z * v[j].z + v[j].w * v[j].w); }
;     const float rs = rsqrtf(wave_sum(s, lane) * (1.f / DM) + EPS);
; __global__ void __launch_bounds__(512) mega_fwd(Params P) {
;     ...
;         for (int m = gw; m < 2048; m += NGW) { const float* src = (m < 1024) ? pp->in[2] + (size_t)m * DM : pp->in[3] + (size_t)(m - 1024) * DM; norm_row(src, g_mem, MN + (size_t)m * DM, nullptr, lane); }
.LBB0_190:
	global_load_dwordx4 v[24:27], v194, s[42:43]
	global_load_dwordx4 v[28:31], v194, s[42:43] offset:1024
	global_load_dwordx4 v[32:35], v194, s[42:43] offset:2048
	global_load_dwordx4 v[36:39], v194, s[42:43] offset:3072
	v_lshl_add_u64 v[0:1], s[42:43], 0, v[194:195]
	s_movk_i32 s29, 0x1000
	v_add_co_u32_e32 v48, vcc, s29, v0
	s_lshl_b64 s[40:41], s[40:41], 12
	s_nop 0
	v_addc_co_u32_e32 v49, vcc, 0, v1, vcc
	global_load_dwordx4 v[40:43], v[48:49], off
	global_load_dwordx4 v[44:47], v[48:49], off offset:1024
	global_load_dwordx4 v[0:3], v[48:49], off offset:3072
	s_nop 0
	global_load_dwordx4 v[48:51], v[48:49], off offset:2048
	s_nop 0
	global_load_dwordx4 v[52:55], v[6:7], off
	s_add_u32 s48, s48, s50
	s_addc_u32 s49, s49, s51
	s_add_u32 s36, s36, s38
	s_addc_u32 s37, s37, s39
	s_cmpk_lt_i32 s48, 0x800
	s_waitcnt vmcnt(0)
	v_mov_b32_e32 v58, v25
	s_waitcnt vmcnt(7)
	v_mov_b32_e32 v59, v29
	v_mov_b32_e32 v62, v27
	v_mov_b32_e32 v63, v31
	v_mov_b32_e32 v56, v24
	v_mov_b32_e32 v57, v28
	v_mov_b32_e32 v60, v26
	v_mov_b32_e32 v61, v30
	s_waitcnt vmcnt(6)
	v_pk_mul_f32 v[64:65], v[34:35], v[34:35]
	v_pk_mul_f32 v[66:67], v[32:33], v[32:33]
	v_pk_mul_f32 v[58:59], v[58:59], v[58:59]
	v_pk_mul_f32 v[62:63], v[62:63], v[62:63]
	v_pk_mov_b32 v[70:71], v[66:67], v[64:65] op_sel:[1,0]
	v_mov_b32_e32 v67, v65
	v_pk_fma_f32 v[56:57], v[56:57], v[56:57], v[58:59]
	v_pk_fma_f32 v[58:59], v[60:61], v[60:61], v[62:63]
	s_waitcnt vmcnt(5)
	v_mul_f32_e32 v8, v37, v37
	v_mul_f32_e32 v68, v39, v39
	v_pk_add_f32 v[60:61], v[70:71], v[66:67]
	v_pk_add_f32 v[56:57], v[56:57], v[58:59]
	v_pk_fma_f32 v[64:65], v[36:37], v[36:37], v[8:9] op_sel_hi:[1,1,0]
	v_pk_fma_f32 v[68:69], v[38:39], v[38:39], v[68:69] op_sel_hi:[1,1,0]
	s_waitcnt vmcnt(4)
	v_mul_f32_e32 v23, v40, v40
	v_mul_f32_e32 v72, v41, v41
	v_pk_add_f32 v[58:59], v[60:61], v[60:61] op_sel:[0,1] op_sel_hi:[1,0]
	v_pk_add_f32 v[56:57], v[56:57], v[56:57] op_sel:[0,1] op_sel_hi:[1,0]
	v_mul_f32_e32 v65, v42, v42
	v_mul_f32_e32 v69, v43, v43
	s_waitcnt vmcnt(3)
	v_pk_mul_f32 v[62:63], v[46:47], v[46:47]
	v_pk_mul_f32 v[66:67], v[44:45], v[44:45]
	v_mov_b32_e32 v59, v72
	v_mov_b32_e32 v57, v23
	v_pk_mov_b32 v[60:61], v[66:67], v[62:63] op_sel:[1,0]
	v_mov_b32_e32 v67, v63
	v_pk_add_f32 v[64:65], v[64:65], v[68:69]
	v_pk_add_f32 v[56:57], v[56:57], v[58:59]
	s_waitcnt vmcnt(1)
	v_mul_f32_e32 v8, v49, v49
	v_mul_f32_e32 v70, v51, v51
	v_pk_add_f32 v[60:61], v[60:61], v[66:67]
	v_pk_add_f32 v[56:57], v[56:57], v[64:65]
	v_mul_f32_e32 v73, v0, v0
	v_mul_f32_e32 v74, v1, v1
	v_mul_f32_e32 v75, v2, v2
	v_mul_f32_e32 v76, v3, v3
	v_pk_fma_f32 v[62:63], v[48:49], v[48:49], v[8:9] op_sel_hi:[1,1,0]
	v_pk_fma_f32 v[70:71], v[50:51], v[50:51], v[70:71] op_sel_hi:[1,1,0]
	v_pk_add_f32 v[60:61], v[60:61], v[60:61] op_sel:[0,1] op_sel_hi:[1,0]
	v_pk_add_f32 v[56:57], v[56:57], v[56:57] op_sel:[0,1] op_sel_hi:[1,0]
	v_mov_b32_e32 v63, v75
	v_mov_b32_e32 v71, v76
	v_mov_b32_e32 v61, v74
	v_mov_b32_e32 v57, v73
	v_pk_add_f32 v[62:63], v[62:63], v[70:71]
	v_pk_add_f32 v[56:57], v[56:57], v[60:61]
	s_nop 0
	v_pk_add_f32 v[56:57], v[56:57], v[62:63]
	s_nop 0
	v_add_f32_e32 v8, v56, v57
	s_nop 1
	v_mov_b32_dpp v23, v8 quad_perm:[1,0,3,2] row_mask:0xf bank_mask:0xf
	v_lshl_add_u64 v[56:57], v[4:5], 0, s[40:41]
	s_waitcnt lgkmcnt(0)
	v_add_f32_e32 v8, v8, v23
	s_nop 1
	v_mov_b32_dpp v23, v8 quad_perm:[2,3,0,1] row_mask:0xf bank_mask:0xf
	s_waitcnt lgkmcnt(0)
	v_add_f32_e32 v8, v8, v23
	s_nop 1
	v_mov_b32_dpp v23, v8 row_half_mirror row_mask:0xf bank_mask:0xf
	s_waitcnt lgkmcnt(0)
	v_add_f32_e32 v8, v8, v23
	s_nop 1
	v_mov_b32_dpp v23, v8 row_mirror row_mask:0xf bank_mask:0xf
	s_waitcnt lgkmcnt(0)
	v_add_f32_e32 v8, v8, v23
	v_mov_b32_e32 v23, v8
	s_nop 1
	v_permlane16_swap_b32_e32 v23, v8
	s_waitcnt lgkmcnt(0)
; __device__ __forceinline__ unsigned cvt_pk_bf16(float lo, float hi) { unsigned r; asm volatile("v_cvt_pk_bf16_f32 %0, %1, %2" : "=v"(r) : "v"(lo), "v"(hi)); return r; }
; __device__ __forceinline__ void norm_row(const float* xrow, const float* g, bf16_t* orow, float* copy, int lane) {
;     ...
;     const float rs = rsqrtf(wave_sum(s, lane) * (1.f / DM) + EPS);
;     u32x2* o8 = (u32x2*)orow + lane; const f32x4* gr = (const f32x4*)g + lane;
; #pragma unroll
;     for (int j = 0; j < 8; ++j) { const f32x4 gv = gr[64 * j]; u32x2 w; w.x = cvt_pk_bf16(v[j].x * rs * gv.x, v[j].y * rs * gv.y); w.y = cvt_pk_bf16(v[j].z * rs * gv.z, v[j].w * rs * gv.w); o8[64 * j] = w; }
	v_add_f32_e32 v8, v8, v23
	v_mov_b32_e32 v23, v8
	s_nop 1
	v_permlane32_swap_b32_e32 v23, v8
	s_waitcnt lgkmcnt(0)
	v_add_f32_e32 v8, v8, v23
	v_fmamk_f32 v8, v8, 0x3a000000, v196
	v_mul_f32_e32 v23, 0x4b800000, v8
	v_cmp_gt_f32_e32 vcc, s78, v8
	s_nop 1
	v_cndmask_b32_e32 v8, v8, v23, vcc
	v_rsq_f32_e32 v8, v8
	s_nop 0
	v_mul_f32_e32 v23, 0x45800000, v8
	v_cndmask_b32_e32 v8, v8, v23, vcc
	v_mul_f32_e32 v23, v24, v8
	v_mul_f32_e32 v24, v25, v8
	v_mul_f32_e32 v25, v26, v8
	v_mul_f32_e32 v26, v27, v8
	s_waitcnt vmcnt(0)
	v_mul_f32_e32 v24, v53, v24
	v_mul_f32_e32 v25, v54, v25
	v_mul_f32_e32 v23, v52, v23
	v_mul_f32_e32 v26, v55, v26
	v_cvt_pk_bf16_f32 v24, v23, v24
	v_cvt_pk_bf16_f32 v25, v25, v26
	global_store_dwordx2 v[56:57], v[24:25], off
	global_load_dwordx4 v[24:27], v[6:7], off offset:1024
	v_mul_f32_e32 v23, v28, v8
	v_mul_f32_e32 v28, v29, v8
	v_mul_f32_e32 v29, v30, v8
	v_mul_f32_e32 v30, v31, v8
	v_mul_f32_e32 v0, v0, v8
	v_mul_f32_e32 v1, v1, v8
	v_mul_f32_e32 v2, v2, v8
	v_mul_f32_e32 v3, v3, v8
	s_waitcnt vmcnt(0)
	v_mul_f32_e32 v23, v24, v23
	v_mul_f32_e32 v24, v25, v28
	v_mul_f32_e32 v25, v26, v29
	v_mul_f32_e32 v26, v27, v30
	v_cvt_pk_bf16_f32 v24, v23, v24
	v_cvt_pk_bf16_f32 v25, v25, v26
	global_store_dwordx2 v[56:57], v[24:25], off offset:512
	global_load_dwordx4 v[24:27], v[6:7], off offset:2048
	v_mul_f32_e32 v23, v32, v8
	v_mul_f32_e32 v28, v33, v8
	v_mul_f32_e32 v29, v34, v8
	v_mul_f32_e32 v30, v35, v8
	s_waitcnt vmcnt(0)
	v_mul_f32_e32 v23, v24, v23
	v_mul_f32_e32 v24, v25, v28
	v_mul_f32_e32 v25, v26, v29
	v_mul_f32_e32 v26, v27, v30
	v_cvt_pk_bf16_f32 v24, v23, v24
	v_cvt_pk_bf16_f32 v25, v25, v26
	global_store_dwordx2 v[56:57], v[24:25], off offset:1024
	global_load_dwordx4 v[24:27], v[6:7], off offset:3072
	v_mul_f32_e32 v23, v36, v8
	v_mul_f32_e32 v28, v37, v8
	v_mul_f32_e32 v29, v38, v8
	v_mul_f32_e32 v30, v39, v8
	s_waitcnt vmcnt(0)
	v_mul_f32_e32 v23, v23, v24
	v_mul_f32_e32 v24, v28, v25
	v_mul_f32_e32 v25, v29, v26
	v_mul_f32_e32 v26, v30, v27
	v_cvt_pk_bf16_f32 v24, v23, v24
	v_cvt_pk_bf16_f32 v25, v25, v26
	global_store_dwordx2 v[56:57], v[24:25], off offset:1536
	global_load_dwordx4 v[24:27], v[10:11], off
	v_mul_f32_e32 v23, v40, v8
	v_mul_f32_e32 v28, v41, v8
	v_mul_f32_e32 v29, v42, v8
	v_mul_f32_e32 v30, v43, v8
	s_waitcnt vmcnt(0)
	v_mul_f32_e32 v23, v23, v24
	v_mul_f32_e32 v24, v28, v25
	v_mul_f32_e32 v25, v29, v26
	v_mul_f32_e32 v26, v30, v27
	v_cvt_pk_bf16_f32 v24, v23, v24
	v_cvt_pk_bf16_f32 v25, v25, v26
	global_store_dwordx2 v[56:57], v[24:25], off offset:2048
	global_load_dwordx4 v[24:27], v[12:13], off
	v_mul_f32_e32 v23, v44, v8
	v_mul_f32_e32 v28, v45, v8
	v_mul_f32_e32 v29, v46, v8
	v_mul_f32_e32 v30, v47, v8
	s_waitcnt vmcnt(0)
	v_mul_f32_e32 v23, v23, v24
	v_mul_f32_e32 v24, v28, v25
	v_mul_f32_e32 v25, v29, v26
	v_mul_f32_e32 v26, v30, v27
	v_cvt_pk_bf16_f32 v24, v23, v24
	v_cvt_pk_bf16_f32 v25, v25, v26
	global_store_dwordx2 v[56:57], v[24:25], off offset:2560
	global_load_dwordx4 v[24:27], v[14:15], off
	v_mul_f32_e32 v23, v48, v8
	v_mul_f32_e32 v28, v49, v8
	v_mul_f32_e32 v29, v50, v8
	v_mul_f32_e32 v30, v51, v8
	s_waitcnt vmcnt(0)
	v_mul_f32_e32 v23, v23, v24
	v_mul_f32_e32 v24, v28, v25
	v_mul_f32_e32 v25, v29, v26
	v_mul_f32_e32 v26, v30, v27
	v_cvt_pk_bf16_f32 v24, v23, v24
	v_cvt_pk_bf16_f32 v25, v25, v26
	global_store_dwordx2 v[56:57], v[24:25], off offset:3072
	global_load_dwordx4 v[24:27], v[16:17], off
	s_waitcnt vmcnt(0)
	v_mul_f32_e32 v0, v0, v24
	v_mul_f32_e32 v1, v1, v25
	v_mul_f32_e32 v2, v2, v26
	v_mul_f32_e32 v3, v3, v27
	v_cvt_pk_bf16_f32 v0, v0, v1
	v_cvt_pk_bf16_f32 v1, v2, v3
	global_store_dwordx2 v[56:57], v[0:1], off offset:3584
	s_cbranch_scc0 .LBB0_195

; __device__ __forceinline__ unsigned cvt_pk_bf16(float lo, float hi) { unsigned r; asm volatile("v_cvt_pk_bf16_f32 %0, %1, %2" : "=v"(r) : "v"(lo), "v"(hi)); return r; }
; __device__ __forceinline__ float bf2f(unsigned short h) { return __uint_as_float(((unsigned)h) << 16); }
; __device__ __forceinline__ float bflo(unsigned w) { return __uint_as_float(w << 16); }
; __device__ __forceinline__ float bfhi(unsigned w) { return __uint_as_float(w & 0xffff0000u); }
; __global__ void __launch_bounds__(512) mega_fwd(Params P) {
;     ...
;             for (int part = 0; part < 2; ++part) { const u32x4 w = part ? wk : wq; float v[8] = {bflo(w.x), bfhi(w.x), bflo(w.y), bfhi(w.y), bflo(w.z), bfhi(w.z), bflo(w.w), bfhi(w.w)};
;                 float ss = 0.f;
; #pragma unroll
;                 for (int e = 0; e < 8; ++e) ss += v[e] * v[e];
;                 const float rs = rsqrtf(wave_sum(ss, lane) * (1.f / 512.f) + EPS); const float* gg = (part ? g_kv : g_q) + lane * 8; const f32x4 g0 = *(const f32x4*)gg, g1 = *(const f32x4*)(gg + 4);
;                 u32x4 o; o.x = cvt_pk_bf16(v[0] * rs * g0.x, v[1] * rs * g0.y); o.y = cvt_pk_bf16(v[2] * rs * g0.z, v[3] * rs * g0.w); o.z = cvt_pk_bf16(v[4] * rs * g1.x, v[5] * rs * g1.y); o.w = cvt_pk_bf16(v[6] * rs * g1.z, v[7] * rs * g1.w);
;                 *(u32x4*)((part ? CKVN : CQN) + (size_t)m * 512 + lane * 8) = o; }
;             { const float x1 = bf2f(kx1), x2 = bf2f(kx2); const float o1 = x1 * cs.x - x2 * cs.y, o2 = x2 * cs.x + x1 * cs.y;
;               bf16_t* kr2 = KR2 + (size_t)m * 64; if (lane < 32) { kr2[lane] = (bf16_t)(cvt_pk_bf16(o1, o1) & 0xffff); kr2[32 + lane] = (bf16_t)(cvt_pk_bf16(o2, o2) & 0xffff); } }
.LBB0_503:
	s_waitcnt vmcnt(4)
	v_and_b32_e32 v56, 0xffff0000, v20
	v_lshlrev_b32_e32 v49, 16, v20
	v_mul_f32_e32 v50, v56, v56
	v_lshlrev_b32_e32 v57, 16, v21
	v_fmac_f32_e32 v50, v49, v49
	v_and_b32_e32 v58, 0xffff0000, v21
	v_fmac_f32_e32 v50, v57, v57
	v_lshlrev_b32_e32 v36, 16, v22
	v_and_b32_e32 v37, 0xffff0000, v22
	v_fmac_f32_e32 v50, v58, v58
	v_pk_mul_f32 v[20:21], v[36:37], v[36:37]
	v_lshlrev_b32_e32 v54, 16, v23
	v_add_f32_e32 v20, v50, v20
	v_and_b32_e32 v55, 0xffff0000, v23
	v_add_f32_e32 v22, v20, v21
	v_pk_mul_f32 v[20:21], v[54:55], v[54:55]
	s_mov_b32 s38, 0x28400000
	v_add_f32_e32 v20, v22, v20
	v_add_f32_e32 v20, v20, v21
	s_nop 1
	v_mov_b32_dpp v21, v20 quad_perm:[1,0,3,2] row_mask:0xf bank_mask:0xf
	s_waitcnt lgkmcnt(0)
	v_add_f32_e32 v20, v20, v21
	s_nop 1
	v_mov_b32_dpp v21, v20 quad_perm:[2,3,0,1] row_mask:0xf bank_mask:0xf
	s_waitcnt lgkmcnt(0)
	v_add_f32_e32 v20, v20, v21
	s_nop 1
	v_mov_b32_dpp v21, v20 row_half_mirror row_mask:0xf bank_mask:0xf
	s_waitcnt lgkmcnt(0)
	v_add_f32_e32 v20, v20, v21
	s_nop 1
	v_mov_b32_dpp v21, v20 row_mirror row_mask:0xf bank_mask:0xf
	s_waitcnt lgkmcnt(0)
	v_add_f32_e32 v20, v20, v21
	v_mov_b32_e32 v21, v20
	s_nop 1
	v_permlane16_swap_b32_e32 v21, v20
	s_waitcnt lgkmcnt(0)
	v_add_f32_e32 v20, v20, v21
	v_mov_b32_e32 v21, v20
	s_nop 1
	v_permlane32_swap_b32_e32 v21, v20
	s_waitcnt lgkmcnt(0)
	v_add_f32_e32 v20, v20, v21
	v_fmamk_f32 v20, v20, 0x3b000000, v196
	v_cmp_gt_f32_e32 vcc, s78, v20
	v_mul_f32_e32 v21, 0x4b800000, v20
	s_nop 0
	v_cndmask_b32_e32 v20, v20, v21, vcc
	v_rsq_f32_e32 v20, v20
	s_nop 0
	v_mul_f32_e32 v21, 0x45800000, v20
	v_cndmask_b32_e32 v59, v20, v21, vcc
	global_load_dwordx4 v[50:53], v[24:25], off offset:16
	global_load_dwordx4 v[20:23], v[24:25], off
	v_mul_f32_e32 v49, v59, v49
	s_waitcnt vmcnt(0)
	v_mul_f32_e32 v20, v49, v20
	v_mul_f32_e32 v49, v59, v56
	v_mul_f32_e32 v21, v49, v21
	v_cvt_pk_bf16_f32 v20, v20, v21
	v_mul_f32_e32 v21, v59, v57
	v_mul_f32_e32 v21, v21, v22
	v_mul_f32_e32 v22, v59, v58
	v_mul_f32_e32 v22, v22, v23
	v_cvt_pk_bf16_f32 v21, v21, v22
	v_mul_f32_e32 v22, v59, v36
	v_mul_f32_e32 v23, v59, v37
	v_mul_f32_e32 v22, v22, v50
	v_mul_f32_e32 v23, v23, v51
	v_cvt_pk_bf16_f32 v22, v22, v23
	v_mul_f32_e32 v23, v59, v54
	v_mul_f32_e32 v36, v59, v55
	v_mul_f32_e32 v23, v23, v52
	v_mul_f32_e32 v36, v36, v53
	v_cvt_pk_bf16_f32 v23, v23, v36
	v_lshl_add_u64 v[36:37], s[48:49], 0, v[28:29]
	v_add_co_u32_e32 v50, vcc, s38, v36
	v_and_b32_e32 v56, 0xffff0000, v16
	s_nop 0
	v_addc_co_u32_e32 v51, vcc, 0, v37, vcc
	global_store_dwordx4 v[50:51], v[20:23], off
	s_load_dwordx2 s[38:39], s[46:47], 0x60
	v_lshlrev_b32_e32 v49, 16, v16
	v_mul_f32_e32 v20, v56, v56
	v_lshlrev_b32_e32 v57, 16, v17
	v_fmac_f32_e32 v20, v49, v49
	v_and_b32_e32 v58, 0xffff0000, v17
	v_fmac_f32_e32 v20, v57, v57
	v_lshlrev_b32_e32 v22, 16, v18
	v_and_b32_e32 v23, 0xffff0000, v18
	v_fmac_f32_e32 v20, v58, v58
	v_pk_mul_f32 v[16:17], v[22:23], v[22:23]
	v_lshlrev_b32_e32 v54, 16, v19
	v_add_f32_e32 v16, v20, v16
	v_and_b32_e32 v55, 0xffff0000, v19
	s_waitcnt lgkmcnt(0)
	s_add_u32 s38, s38, s58
	v_add_f32_e32 v18, v16, v17
	v_pk_mul_f32 v[16:17], v[54:55], v[54:55]
	s_addc_u32 s39, s39, s59
	v_add_f32_e32 v16, v18, v16
	global_load_dwordx4 v[18:21], v194, s[38:39] offset:16
	global_load_dwordx4 v[50:53], v194, s[38:39]
	v_add_f32_e32 v16, v16, v17
	s_nop 1
	v_mov_b32_dpp v17, v16 quad_perm:[1,0,3,2] row_mask:0xf bank_mask:0xf
	s_waitcnt lgkmcnt(0)
	v_add_f32_e32 v16, v16, v17
	s_nop 1
	v_mov_b32_dpp v17, v16 quad_perm:[2,3,0,1] row_mask:0xf bank_mask:0xf
	s_waitcnt lgkmcnt(0)
	v_add_f32_e32 v16, v16, v17
	s_nop 1
	v_mov_b32_dpp v17, v16 row_half_mirror row_mask:0xf bank_mask:0xf
	s_waitcnt lgkmcnt(0)
	v_add_f32_e32 v16, v16, v17
	s_nop 1
	v_mov_b32_dpp v17, v16 row_mirror row_mask:0xf bank_mask:0xf
	s_waitcnt lgkmcnt(0)
	v_add_f32_e32 v16, v16, v17
	v_mov_b32_e32 v17, v16
	s_nop 1
	v_permlane16_swap_b32_e32 v17, v16
	s_waitcnt lgkmcnt(0)
	v_add_f32_e32 v16, v16, v17
	v_mov_b32_e32 v17, v16
	s_nop 1
	v_permlane32_swap_b32_e32 v17, v16
	s_waitcnt lgkmcnt(0)
	v_add_f32_e32 v16, v16, v17
	v_fmamk_f32 v16, v16, 0x3b000000, v196
	v_cmp_gt_f32_e32 vcc, s78, v16
	v_mul_f32_e32 v17, 0x4b800000, v16
	s_nop 0
	v_cndmask_b32_e32 v16, v16, v17, vcc
	v_rsq_f32_e32 v16, v16
	s_nop 0
	v_mul_f32_e32 v17, 0x45800000, v16
	v_cndmask_b32_e32 v59, v16, v17, vcc
	v_mul_f32_e32 v16, v59, v49
	v_mul_f32_e32 v17, v59, v56
	v_mul_f32_e32 v22, v59, v22
	v_mul_f32_e32 v49, v59, v58
	s_waitcnt vmcnt(1)
	v_mul_f32_e32 v18, v22, v18
	s_waitcnt vmcnt(0)
	v_mul_f32_e32 v16, v16, v50
	v_mul_f32_e32 v17, v17, v51
	v_cvt_pk_bf16_f32 v16, v16, v17
	v_mul_f32_e32 v17, v59, v57
	v_mul_f32_e32 v22, v59, v23
	v_mul_f32_e32 v17, v17, v52
	v_mul_f32_e32 v19, v22, v19
	v_mul_f32_e32 v49, v49, v53
	v_cvt_pk_bf16_f32 v17, v17, v49
	v_cvt_pk_bf16_f32 v18, v18, v19
	v_mul_f32_e32 v19, v59, v54
	v_mul_f32_e32 v19, v19, v20
	v_mul_f32_e32 v20, v59, v55
	v_mul_f32_e32 v20, v20, v21
	v_cvt_pk_bf16_f32 v19, v19, v20
	v_add_co_u32_e32 v20, vcc, 0x2ac00000, v36
	s_nop 1
	v_addc_co_u32_e32 v21, vcc, 0, v37, vcc
	global_store_dwordx4 v[20:21], v[16:19], off
	s_and_saveexec_b64 s[64:65], s[42:43]
	s_cbranch_execz .LBB0_494
	v_lshlrev_b32_e32 v16, 16, v48
	v_lshlrev_b32_e32 v17, 16, v47
	v_mul_f32_e32 v18, v38, v16
	v_mul_f32_e32 v16, v39, v16
	v_fma_f32 v16, v38, v17, -v16
	v_fmac_f32_e32 v18, v39, v17
	v_cvt_pk_bf16_f32 v19, v16, v16
	v_lshl_add_u64 v[16:17], s[48:49], 0, v[30:31]
	v_add_co_u32_e32 v16, vcc, 0x3f200000, v16
	s_nop 1
	v_addc_co_u32_e32 v17, vcc, 0, v17, vcc
	global_store_short v[16:17], v19, off
	v_cvt_pk_bf16_f32 v18, v18, v18
	global_store_short v[16:17], v18, off offset:64
	s_branch .LBB0_494

; __device__ __forceinline__ float bflo(unsigned w) { return __uint_as_float(w << 16); }
; __device__ __forceinline__ float bfhi(unsigned w) { return __uint_as_float(w & 0xffff0000u); }
; __global__ void __launch_bounds__(512) mega_fwd(Params P) {
;     ...
;         for (int m = gw; m < MTOK; m += NGW) {
;             bf16_t* yn = XN + (size_t)m * 2048;
;             const u32x4 wa = *(const u32x4*)(YA + (size_t)m * 768 + lane * 8), wb = *(const u32x4*)(YB + (size_t)m * 768 + lane * 8), wc_ = *(const u32x4*)(YC + (size_t)m * 512 + lane * 8);
;             const u32x2 wa2 = *(const u32x2*)(YA + (size_t)m * 768 + 512 + lane * 4), wb2 = *(const u32x2*)(YB + (size_t)m * 768 + 512 + lane * 4);
; #pragma unroll
;             for (int part = 0; part < 2; ++part) { const float* gg = part ? g_ob : g_oa;
;                 const u32x4 w = part ? wb : wa; const u32x2 w2 = part ? wb2 : wa2;
;                 float v[12] = {bflo(w.x), bfhi(w.x), bflo(w.y), bfhi(w.y), bflo(w.z), bfhi(w.z), bflo(w.w), bfhi(w.w), bflo(w2.x), bfhi(w2.x), bflo(w2.y), bfhi(w2.y)};
;                 float ss = 0.f;
; #pragma unroll
;                 for (int e = 0; e < 12; ++e) ss += v[e] * v[e];
;                 const float rs = rsqrtf(wave_sum(ss, lane) * (1.f / 768.f) + EPS); const f32x4 g0 = *(const f32x4*)(gg + lane * 8), g1 = *(const f32x4*)(gg + lane * 8 + 4), g2 = *(const f32x4*)(gg + 512 + lane * 4);
.LBB0_1365:
	v_lshl_add_u64 v[30:31], s[52:53], 0, v[16:17]
	v_lshl_add_u64 v[44:45], s[52:53], 0, v[20:21]
	v_lshl_add_u64 v[28:29], s[52:53], 0, v[24:25]
	global_load_dwordx4 v[4:7], v[12:13], off offset:16
	global_load_dwordx4 v[8:11], v[12:13], off
	global_load_dwordx4 v[0:3], v[14:15], off offset:2048
	global_load_dwordx4 v[40:43], v[30:31], off
	v_add_co_u32_e64 v30, s[42:43], s90, v44
	v_lshl_add_u64 v[46:47], s[52:53], 0, v[18:19]
	v_add_co_u32_e32 v48, vcc, 0x1df00000, v28
	v_addc_co_u32_e64 v31, s[42:43], 0, v45, s[42:43]
	v_add_co_u32_e64 v52, s[42:43], s90, v46
	v_addc_co_u32_e32 v49, vcc, 0, v29, vcc
	s_nop 0
	v_addc_co_u32_e64 v53, s[42:43], 0, v47, s[42:43]
	global_load_dwordx4 v[44:47], v[48:49], off
	v_add_co_u32_e32 v28, vcc, 0x28400000, v28
	v_lshl_add_u64 v[26:27], s[52:53], 0, v[22:23]
	s_nop 0
	v_addc_co_u32_e32 v29, vcc, 0, v29, vcc
	s_mov_b32 s38, 0x1df00000
	v_add_co_u32_e32 v54, vcc, s38, v26
	global_load_dwordx4 v[48:51], v[28:29], off
	s_nop 0
	v_addc_co_u32_e32 v55, vcc, 0, v27, vcc
	v_add_co_u32_e32 v26, vcc, 0x28400000, v26
	v_lshl_add_u64 v[16:17], v[16:17], 0, s[54:55]
	s_nop 0
	v_addc_co_u32_e32 v27, vcc, 0, v27, vcc
	global_load_dwordx2 v[26:27], v[26:27], off offset:1024
	v_lshl_add_u64 v[18:19], v[18:19], 0, s[56:57]
	global_load_dwordx2 v[28:29], v[54:55], off offset:1024
	v_lshl_add_u64 v[20:21], v[20:21], 0, s[56:57]
	v_lshl_add_u64 v[22:23], v[22:23], 0, s[58:59]
	v_lshl_add_u64 v[24:25], v[24:25], 0, s[58:59]
	s_waitcnt vmcnt(4)
	v_lshlrev_b32_e32 v60, 16, v41
	v_and_b32_e32 v61, 0xffff0000, v41
	v_and_b32_e32 v59, 0xffff0000, v40
	v_lshlrev_b32_e32 v58, 16, v40
	v_lshlrev_b32_e32 v40, 16, v42
	s_waitcnt vmcnt(3)
	v_and_b32_e32 v62, 0xffff0000, v44
	v_lshlrev_b32_e32 v41, 16, v44
	v_mul_f32_e32 v69, v62, v62
	v_lshlrev_b32_e32 v63, 16, v45
	v_fmac_f32_e32 v69, v41, v41
	v_and_b32_e32 v64, 0xffff0000, v45
	v_fmac_f32_e32 v69, v63, v63
	v_lshlrev_b32_e32 v65, 16, v46
	v_fmac_f32_e32 v69, v64, v64
	v_and_b32_e32 v66, 0xffff0000, v46
	v_fmac_f32_e32 v69, v65, v65
	v_lshlrev_b32_e32 v67, 16, v47
	v_fmac_f32_e32 v69, v66, v66
	v_and_b32_e32 v68, 0xffff0000, v47
	v_fmac_f32_e32 v69, v67, v67
	v_fmac_f32_e32 v69, v68, v68
	s_waitcnt vmcnt(2)
	v_lshlrev_b32_e32 v70, 16, v48
	v_and_b32_e32 v71, 0xffff0000, v48
	v_lshlrev_b32_e32 v72, 16, v49
	s_waitcnt vmcnt(0)
	v_lshlrev_b32_e32 v44, 16, v28
	v_and_b32_e32 v45, 0xffff0000, v28
	v_pk_mul_f32 v[46:47], v[44:45], v[44:45]
	v_lshlrev_b32_e32 v28, 16, v29
	v_and_b32_e32 v29, 0xffff0000, v29
	v_add_f32_e32 v46, v69, v46
	v_and_b32_e32 v73, 0xffff0000, v49
	v_pk_mul_f32 v[48:49], v[28:29], v[28:29]
	v_add_f32_e32 v46, v46, v47
	v_add_f32_e32 v46, v46, v48
	v_add_f32_e32 v46, v46, v49
	s_nop 1
	v_mov_b32_dpp v48, v46 quad_perm:[1,0,3,2] row_mask:0xf bank_mask:0xf
	v_mul_f32_e32 v78, v71, v71
	v_fmac_f32_e32 v78, v70, v70
	v_fmac_f32_e32 v78, v72, v72
	v_lshlrev_b32_e32 v74, 16, v50
	s_waitcnt lgkmcnt(0)
	v_add_f32_e32 v46, v46, v48
	s_nop 1
	v_mov_b32_dpp v48, v46 quad_perm:[2,3,0,1] row_mask:0xf bank_mask:0xf
	v_fmac_f32_e32 v78, v73, v73
	v_and_b32_e32 v75, 0xffff0000, v50
	v_fmac_f32_e32 v78, v74, v74
	v_lshlrev_b32_e32 v76, 16, v51
	s_waitcnt lgkmcnt(0)
	v_add_f32_e32 v46, v46, v48
	s_nop 1
	v_mov_b32_dpp v48, v46 row_half_mirror row_mask:0xf bank_mask:0xf
	v_fmac_f32_e32 v78, v75, v75
	v_and_b32_e32 v77, 0xffff0000, v51
	v_lshlrev_b32_e32 v50, 16, v26
	v_and_b32_e32 v51, 0xffff0000, v26
	s_waitcnt lgkmcnt(0)
	v_add_f32_e32 v46, v46, v48
	s_nop 1
	v_mov_b32_dpp v48, v46 row_mirror row_mask:0xf bank_mask:0xf
	v_fmac_f32_e32 v78, v76, v76
	v_pk_mul_f32 v[54:55], v[50:51], v[50:51]
	v_fmac_f32_e32 v78, v77, v77
	v_lshlrev_b32_e32 v26, 16, v27
	s_waitcnt lgkmcnt(0)
	v_add_f32_e32 v46, v46, v48
	v_mov_b32_e32 v48, v46
	s_nop 1
	v_permlane16_swap_b32_e32 v48, v46
	v_and_b32_e32 v27, 0xffff0000, v27
	v_add_f32_e32 v47, v78, v54
	v_pk_mul_f32 v[56:57], v[26:27], v[26:27]
	v_add_f32_e32 v47, v47, v55
	s_waitcnt lgkmcnt(0)
	v_add_f32_e32 v46, v46, v48
	v_mov_b32_e32 v48, v46
	s_nop 1
	v_permlane32_swap_b32_e32 v48, v46
	v_add_f32_e32 v47, v47, v56
	v_add_f32_e32 v47, v47, v57
	s_nop 1
	v_mov_b32_dpp v49, v47 quad_perm:[1,0,3,2] row_mask:0xf bank_mask:0xf
	s_waitcnt lgkmcnt(0)
	v_add_f32_e32 v46, v46, v48
	v_fmamk_f32 v46, v46, 0x3aaaaaab, v196
	v_mul_f32_e32 v48, 0x4b800000, v46
	v_cmp_gt_f32_e32 vcc, s78, v46
	s_waitcnt lgkmcnt(0)
; __device__ __forceinline__ unsigned cvt_pk_bf16(float lo, float hi) { unsigned r; asm volatile("v_cvt_pk_bf16_f32 %0, %1, %2" : "=v"(r) : "v"(lo), "v"(hi)); return r; }
; __global__ void __launch_bounds__(512) mega_fwd(Params P) {
;     ...
;             for (int part = 0; part < 2; ++part) { const float* gg = part ? g_ob : g_oa;
;                 const u32x4 w = part ? wb : wa; const u32x2 w2 = part ? wb2 : wa2;
;                 float v[12] = {bflo(w.x), bfhi(w.x), bflo(w.y), bfhi(w.y), bflo(w.z), bfhi(w.z), bflo(w.w), bfhi(w.w), bflo(w2.x), bfhi(w2.x), bflo(w2.y), bfhi(w2.y)};
;                 float ss = 0.f;
; #pragma unroll
;                 for (int e = 0; e < 12; ++e) ss += v[e] * v[e];
;                 const float rs = rsqrtf(wave_sum(ss, lane) * (1.f / 768.f) + EPS); const f32x4 g0 = *(const f32x4*)(gg + lane * 8), g1 = *(const f32x4*)(gg + lane * 8 + 4), g2 = *(const f32x4*)(gg + 512 + lane * 4);
;                 u32x4 o; o.x = cvt_pk_bf16(v[0] * rs * g0.x, v[1] * rs * g0.y); o.y = cvt_pk_bf16(v[2] * rs * g0.z, v[3] * rs * g0.w); o.z = cvt_pk_bf16(v[4] * rs * g1.x, v[5] * rs * g1.y); o.w = cvt_pk_bf16(v[6] * rs * g1.z, v[7] * rs * g1.w);
;                 u32x2 o2; o2.x = cvt_pk_bf16(v[8] * rs * g2.x, v[9] * rs * g2.y); o2.y = cvt_pk_bf16(v[10] * rs * g2.z, v[11] * rs * g2.w);
;     ...
;                 if (part == 0) { o = (u32x4){0u,0u,0u,0u}; o2 = (u32x2){0u,0u}; }
;     ...
;                 if (part == 1) { o = (u32x4){0u,0u,0u,0u}; o2 = (u32x2){0u,0u}; }
;     ...
;                 *(u32x4*)(yn + part * 768 + lane * 8) = o; *(u32x2*)(yn + part * 768 + 512 + lane * 4) = o2; }
;             { const u32x4 w = wc_; float v[8] = {bflo(w.x), bfhi(w.x), bflo(w.y), bfhi(w.y), bflo(w.z), bfhi(w.z), bflo(w.w), bfhi(w.w)};
;               float ss = 0.f;
; #pragma unroll
;               for (int e = 0; e < 8; ++e) ss += v[e] * v[e];
;               const float rs = rsqrtf(wave_sum(ss, lane) * (1.f / 512.f) + EPS); const f32x4 g0 = *(const f32x4*)(g_oc + lane * 8), g1 = *(const f32x4*)(g_oc + lane * 8 + 4);
;               u32x4 o; o.x = cvt_pk_bf16(v[0] * rs * g0.x, v[1] * rs * g0.y); o.y = cvt_pk_bf16(v[2] * rs * g0.z, v[3] * rs * g0.w); o.z = cvt_pk_bf16(v[4] * rs * g1.x, v[5] * rs * g1.y); o.w = cvt_pk_bf16(v[6] * rs * g1.z, v[7] * rs * g1.w);
;     ...
;               o = (u32x4){0u,0u,0u,0u};
;     ...
;               *(u32x4*)(yn + 1536 + lane * 8) = o; }
;         }
	v_add_f32_e32 v47, v47, v49
	v_cndmask_b32_e32 v46, v46, v48, vcc
	v_rsq_f32_e32 v46, v46
	s_nop 0
	v_mul_f32_e32 v48, 0x45800000, v46
	v_cndmask_b32_e32 v46, v46, v48, vcc
	v_mul_f32_e32 v41, v46, v41
	v_mul_f32_e32 v48, v46, v62
	v_mul_f32_e32 v49, v46, v63
	v_mul_f32_e32 v54, v46, v64
	v_mul_f32_e32 v55, v46, v65
	v_mul_f32_e32 v56, v46, v66
	v_mul_f32_e32 v57, v46, v67
	v_mul_f32_e32 v62, v46, v68
	v_mul_f32_e32 v44, v46, v44
	v_mul_f32_e32 v45, v46, v45
	v_mul_f32_e32 v28, v46, v28
	v_mul_f32_e32 v29, v46, v29
	v_mul_f32_e32 v8, v8, v41
	v_mul_f32_e32 v9, v9, v48
	v_mul_f32_e32 v10, v10, v49
	v_mul_f32_e32 v11, v11, v54
	v_mul_f32_e32 v4, v4, v55
	v_mul_f32_e32 v5, v5, v56
	v_mul_f32_e32 v6, v6, v57
	v_mul_f32_e32 v7, v7, v62
	v_mul_f32_e32 v41, v0, v44
	v_mul_f32_e32 v44, v1, v45
	v_mul_f32_e32 v28, v2, v28
	v_mul_f32_e32 v29, v3, v29
	v_cvt_pk_bf16_f32 v0, v8, v9
	v_cvt_pk_bf16_f32 v1, v10, v11
	v_cvt_pk_bf16_f32 v2, v4, v5
	v_cvt_pk_bf16_f32 v3, v6, v7
	v_cvt_pk_bf16_f32 v4, v41, v44
	v_cvt_pk_bf16_f32 v5, v28, v29
	global_store_dwordx4 v[30:31], v[0:3], off
	global_store_dwordx2 v[52:53], v[4:5], off offset:1024
	s_load_dwordx4 s[40:43], s[46:47], 0xb0
	s_nop 1
	v_mov_b32_dpp v28, v47 quad_perm:[2,3,0,1] row_mask:0xf bank_mask:0xf
	s_waitcnt lgkmcnt(0)
	s_add_u32 s38, s40, s28
	s_addc_u32 s39, s41, s29
	global_load_dwordx4 v[0:3], v38, s[38:39]
	global_load_dwordx4 v[4:7], v38, s[38:39] offset:16
	global_load_dwordx4 v[8:11], v39, s[38:39] offset:2048
	v_add_f32_e32 v28, v47, v28
	s_nop 1
	v_mov_b32_dpp v29, v28 row_half_mirror row_mask:0xf bank_mask:0xf
	s_add_u32 s38, s42, s60
	s_addc_u32 s39, s43, s61
	s_add_i32 s48, s48, s50
	s_cmp_lt_i32 s48, 0xa000
	s_waitcnt lgkmcnt(0)
	v_add_f32_e32 v28, v28, v29
	s_nop 1
	v_mov_b32_dpp v29, v28 row_mirror row_mask:0xf bank_mask:0xf
	s_waitcnt lgkmcnt(0)
	v_add_f32_e32 v28, v28, v29
	v_mov_b32_e32 v29, v28
	s_nop 1
	v_permlane16_swap_b32_e32 v29, v28
	s_waitcnt lgkmcnt(0)
	v_add_f32_e32 v28, v28, v29
	v_mov_b32_e32 v29, v28
	s_nop 1
	v_permlane32_swap_b32_e32 v29, v28
	s_waitcnt lgkmcnt(0)
	v_add_f32_e32 v28, v28, v29
	v_fmamk_f32 v28, v28, 0x3aaaaaab, v196
	v_mul_f32_e32 v29, 0x4b800000, v28
	v_cmp_gt_f32_e32 vcc, s78, v28
	s_nop 1
	v_cndmask_b32_e32 v28, v28, v29, vcc
	v_rsq_f32_e32 v28, v28
	s_nop 0
	v_mul_f32_e32 v29, 0x45800000, v28
	v_cndmask_b32_e32 v28, v28, v29, vcc
	v_mul_f32_e32 v29, v28, v70
	v_mul_f32_e32 v41, v28, v71
	v_mul_f32_e32 v44, v28, v72
	v_mul_f32_e32 v45, v28, v73
	v_mul_f32_e32 v46, v28, v74
	v_mul_f32_e32 v47, v28, v75
	v_mul_f32_e32 v48, v28, v76
	v_mul_f32_e32 v49, v28, v77
	v_mul_f32_e32 v50, v28, v50
	v_mul_f32_e32 v51, v28, v51
	v_mul_f32_e32 v26, v28, v26
	v_mul_f32_e32 v27, v28, v27
	v_mul_f32_e32 v28, v59, v59
	v_fmac_f32_e32 v28, v58, v58
	v_fmac_f32_e32 v28, v60, v60
	v_fmac_f32_e32 v28, v61, v61
	s_waitcnt vmcnt(2)
	v_mul_f32_e32 v0, v0, v29
	v_mul_f32_e32 v1, v1, v41
	v_mul_f32_e32 v2, v2, v44
	v_mul_f32_e32 v3, v3, v45
	s_waitcnt vmcnt(1)
	v_mul_f32_e32 v4, v4, v46
	v_mul_f32_e32 v5, v5, v47
	v_mul_f32_e32 v6, v6, v48
	v_mul_f32_e32 v7, v7, v49
	v_cvt_pk_bf16_f32 v0, v0, v1
	v_cvt_pk_bf16_f32 v1, v2, v3
	v_cvt_pk_bf16_f32 v2, v4, v5
	v_cvt_pk_bf16_f32 v3, v6, v7
	s_waitcnt vmcnt(0)
	v_mul_f32_e32 v8, v8, v50
	v_mul_f32_e32 v9, v9, v51
	v_mul_f32_e32 v10, v10, v26
	v_mul_f32_e32 v11, v11, v27
	v_cvt_pk_bf16_f32 v4, v8, v9
	v_cvt_pk_bf16_f32 v5, v10, v11
	global_store_dwordx4 v[30:31], v[0:3], off offset:1536
	global_store_dwordx2 v[52:53], v[4:5], off offset:2560
	global_load_dwordx4 v[0:3], v38, s[38:39]
	s_nop 0
	global_load_dwordx4 v[4:7], v38, s[38:39] offset:16
	v_and_b32_e32 v41, 0xffff0000, v42
	v_pk_mul_f32 v[10:11], v[40:41], v[40:41]
	v_lshlrev_b32_e32 v8, 16, v43
	v_and_b32_e32 v9, 0xffff0000, v43
	v_add_f32_e32 v10, v28, v10
	v_pk_mul_f32 v[26:27], v[8:9], v[8:9]
	v_add_f32_e32 v10, v10, v11
	v_add_f32_e32 v10, v10, v26
	v_add_f32_e32 v10, v10, v27
	s_nop 1
	v_mov_b32_dpp v11, v10 quad_perm:[1,0,3,2] row_mask:0xf bank_mask:0xf
	s_waitcnt lgkmcnt(0)
	v_add_f32_e32 v10, v10, v11
	s_nop 1
	v_mov_b32_dpp v11, v10 quad_perm:[2,3,0,1] row_mask:0xf bank_mask:0xf
	s_waitcnt lgkmcnt(0)
	v_add_f32_e32 v10, v10, v11
	s_nop 1
	v_mov_b32_dpp v11, v10 row_half_mirror row_mask:0xf bank_mask:0xf
	s_waitcnt lgkmcnt(0)
	v_add_f32_e32 v10, v10, v11
	s_nop 1
	v_mov_b32_dpp v11, v10 row_mirror row_mask:0xf bank_mask:0xf
	s_waitcnt lgkmcnt(0)
	v_add_f32_e32 v10, v10, v11
	v_mov_b32_e32 v11, v10
	s_nop 1
	v_permlane16_swap_b32_e32 v11, v10
	s_waitcnt lgkmcnt(0)
	v_add_f32_e32 v10, v10, v11
	v_mov_b32_e32 v11, v10
	s_nop 1
	v_permlane32_swap_b32_e32 v11, v10
	s_waitcnt lgkmcnt(0)
	v_add_f32_e32 v10, v10, v11
	v_fmamk_f32 v10, v10, 0x3b000000, v196
	v_mul_f32_e32 v11, 0x4b800000, v10
	v_cmp_gt_f32_e32 vcc, s78, v10
	s_nop 1
	v_cndmask_b32_e32 v10, v10, v11, vcc
	v_rsq_f32_e32 v10, v10
	s_nop 0
	v_mul_f32_e32 v11, 0x45800000, v10
	v_cndmask_b32_e32 v10, v10, v11, vcc
	v_mul_f32_e32 v11, v10, v58
	v_mul_f32_e32 v26, v10, v59
	v_mul_f32_e32 v27, v10, v60
	v_mul_f32_e32 v28, v10, v61
	v_mul_f32_e32 v29, v10, v40
	v_mul_f32_e32 v40, v10, v41
	v_mul_f32_e32 v8, v10, v8
	v_mul_f32_e32 v9, v10, v9
	s_waitcnt vmcnt(1)
	v_mul_f32_e32 v0, v0, v11
	v_mul_f32_e32 v1, v1, v26
	v_mul_f32_e32 v2, v2, v27
	v_mul_f32_e32 v3, v3, v28
	s_waitcnt vmcnt(0)
	v_mul_f32_e32 v4, v4, v29
	v_mul_f32_e32 v5, v5, v40
	v_mul_f32_e32 v6, v6, v8
	v_mul_f32_e32 v7, v7, v9
	v_cvt_pk_bf16_f32 v0, v0, v1
	v_cvt_pk_bf16_f32 v1, v2, v3
	v_cvt_pk_bf16_f32 v2, v4, v5
	v_cvt_pk_bf16_f32 v3, v6, v7
	global_store_dwordx4 v[30:31], v[0:3], off offset:3072
	s_cbranch_scc1 .LBB0_1365

; __device__ __forceinline__ float bflo(unsigned w) { return __uint_as_float(w << 16); }
; __device__ __forceinline__ float bfhi(unsigned w) { return __uint_as_float(w & 0xffff0000u); }
; __global__ void __launch_bounds__(512) mega_fwd(Params P) {
;     ...
;       for (int m = gw; m < MTOK; m += NGW) { const u32x2* xb = (const u32x2*)(XN + (size_t)m * DM) + lane; f32x4* xr = (f32x4*)(X + (size_t)m * DM) + lane; f32x4 v[8]; float s = 0.f;
; #pragma unroll
;         for (int j = 0; j < 8; ++j) { const u32x2 w = xb[64 * j]; v[j] = (f32x4){bflo(w.x), bfhi(w.x), bflo(w.y), bfhi(w.y)}; s += (v[j].x * v[j].x + v[j].y * v[j].y) + (v[j].z * v[j].z + v[j].w * v[j].w); }
.LBB0_1808:
	global_load_dwordx2 v[26:27], v[16:17], off offset:-3584
	global_load_dwordx2 v[28:29], v[16:17], off offset:-3072
	global_load_dwordx2 v[30:31], v[16:17], off offset:-2560
	global_load_dwordx2 v[32:33], v[16:17], off offset:-2048
	global_load_dwordx2 v[34:35], v[16:17], off offset:-1536
	global_load_dwordx2 v[36:37], v[16:17], off offset:-1024
	global_load_dwordx2 v[38:39], v[16:17], off offset:-512
	global_load_dwordx2 v[40:41], v[16:17], off
	global_load_dwordx4 v[0:3], v[4:5], off
	v_add_co_u32_e32 v42, vcc, s3, v14
	s_add_i32 s0, s0, s2
	s_nop 0
	v_addc_co_u32_e32 v43, vcc, -1, v15, vcc
	v_lshl_add_u64 v[16:17], v[16:17], 0, s[6:7]
	s_cmp_lt_i32 s0, 0xa000
	s_waitcnt vmcnt(8)
	v_lshlrev_b32_e32 v44, 16, v26
	v_and_b32_e32 v45, 0xffff0000, v26
	v_lshlrev_b32_e32 v26, 16, v27
	v_and_b32_e32 v27, 0xffff0000, v27
	s_waitcnt vmcnt(7)
	v_lshlrev_b32_e32 v46, 16, v28
	v_and_b32_e32 v47, 0xffff0000, v28
	v_lshlrev_b32_e32 v28, 16, v29
	v_and_b32_e32 v29, 0xffff0000, v29
	s_waitcnt vmcnt(6)
	v_lshlrev_b32_e32 v48, 16, v30
	v_and_b32_e32 v49, 0xffff0000, v30
	v_lshlrev_b32_e32 v30, 16, v31
	v_and_b32_e32 v31, 0xffff0000, v31
	v_mov_b32_e32 v62, v45
	v_mov_b32_e32 v63, v47
	v_mov_b32_e32 v66, v27
	v_mov_b32_e32 v67, v29
	v_mov_b32_e32 v60, v44
	v_mov_b32_e32 v61, v46
	v_mov_b32_e32 v64, v26
	v_mov_b32_e32 v65, v28
	v_mov_b32_e32 v70, v49
	v_mov_b32_e32 v71, v31
	v_pk_mul_f32 v[62:63], v[62:63], v[62:63]
	v_pk_mul_f32 v[66:67], v[66:67], v[66:67]
	s_waitcnt vmcnt(5)
	v_lshlrev_b32_e32 v50, 16, v32
	v_and_b32_e32 v51, 0xffff0000, v32
	v_lshlrev_b32_e32 v32, 16, v33
	v_and_b32_e32 v33, 0xffff0000, v33
	v_mov_b32_e32 v68, v48
	v_mov_b32_e32 v69, v30
	v_pk_mul_f32 v[70:71], v[70:71], v[70:71]
	v_pk_fma_f32 v[60:61], v[60:61], v[60:61], v[62:63]
	v_pk_fma_f32 v[62:63], v[64:65], v[64:65], v[66:67]
	s_waitcnt vmcnt(4)
	v_lshlrev_b32_e32 v52, 16, v34
	v_and_b32_e32 v53, 0xffff0000, v34
	v_lshlrev_b32_e32 v34, 16, v35
	v_and_b32_e32 v35, 0xffff0000, v35
	v_mul_f32_e32 v72, v51, v51
	v_mul_f32_e32 v74, v33, v33
	v_pk_fma_f32 v[64:65], v[68:69], v[68:69], v[70:71]
	v_pk_add_f32 v[60:61], v[60:61], v[62:63]
	s_waitcnt vmcnt(3)
	v_lshlrev_b32_e32 v54, 16, v36
	v_and_b32_e32 v55, 0xffff0000, v36
	v_lshlrev_b32_e32 v36, 16, v37
	v_and_b32_e32 v37, 0xffff0000, v37
	v_pk_mul_f32 v[76:77], v[52:53], v[52:53]
	v_pk_mul_f32 v[78:79], v[34:35], v[34:35]
	v_pk_fma_f32 v[72:73], v[50:51], v[50:51], v[72:73] op_sel_hi:[1,1,0]
	v_pk_fma_f32 v[74:75], v[32:33], v[32:33], v[74:75] op_sel_hi:[1,1,0]
	v_pk_add_f32 v[62:63], v[64:65], v[64:65] op_sel:[0,1] op_sel_hi:[1,0]
	v_pk_add_f32 v[60:61], v[60:61], v[60:61] op_sel:[0,1] op_sel_hi:[1,0]
	v_mov_b32_e32 v82, v55
	v_mov_b32_e32 v83, v37
	v_mov_b32_e32 v73, v78
	v_mov_b32_e32 v75, v79
	v_mov_b32_e32 v63, v77
	v_mov_b32_e32 v61, v76
	s_waitcnt vmcnt(2)
	v_lshlrev_b32_e32 v56, 16, v38
	v_and_b32_e32 v57, 0xffff0000, v38
	v_lshlrev_b32_e32 v38, 16, v39
	v_and_b32_e32 v39, 0xffff0000, v39
	v_mov_b32_e32 v80, v54
	v_mov_b32_e32 v81, v36
	v_pk_mul_f32 v[82:83], v[82:83], v[82:83]
	v_pk_add_f32 v[64:65], v[72:73], v[74:75]
	v_pk_add_f32 v[60:61], v[60:61], v[62:63]
	s_waitcnt vmcnt(1)
	v_lshlrev_b32_e32 v58, 16, v40
	v_and_b32_e32 v59, 0xffff0000, v40
	v_lshlrev_b32_e32 v40, 16, v41
	v_and_b32_e32 v41, 0xffff0000, v41
	v_mul_f32_e32 v84, v57, v57
	v_mul_f32_e32 v86, v39, v39
	v_pk_fma_f32 v[66:67], v[80:81], v[80:81], v[82:83]
	v_pk_add_f32 v[60:61], v[60:61], v[64:65]
	v_pk_mul_f32 v[88:89], v[58:59], v[58:59]
	v_pk_mul_f32 v[90:91], v[40:41], v[40:41]
	v_pk_fma_f32 v[84:85], v[56:57], v[56:57], v[84:85] op_sel_hi:[1,1,0]
	v_pk_fma_f32 v[86:87], v[38:39], v[38:39], v[86:87] op_sel_hi:[1,1,0]
	v_pk_add_f32 v[66:67], v[66:67], v[66:67] op_sel:[0,1] op_sel_hi:[1,0]
	v_pk_add_f32 v[60:61], v[60:61], v[60:61] op_sel:[0,1] op_sel_hi:[1,0]
	v_mov_b32_e32 v85, v90
	v_mov_b32_e32 v87, v91
	v_mov_b32_e32 v67, v89
	v_mov_b32_e32 v61, v88
	v_pk_add_f32 v[68:69], v[84:85], v[86:87]
	v_pk_add_f32 v[60:61], v[60:61], v[66:67]
	s_nop 0
	v_pk_add_f32 v[60:61], v[60:61], v[68:69]
	s_nop 0
	v_add_f32_e32 v25, v60, v61
	s_nop 1
	v_mov_b32_dpp v60, v25 quad_perm:[1,0,3,2] row_mask:0xf bank_mask:0xf
	s_waitcnt lgkmcnt(0)
; __device__ __forceinline__ float bflo(unsigned w) { return __uint_as_float(w << 16); }
; __device__ __forceinline__ float bfhi(unsigned w) { return __uint_as_float(w & 0xffff0000u); }
; __global__ void __launch_bounds__(512) mega_fwd(Params P) {
;     ...
;         for (int j = 0; j < 8; ++j) { const u32x2 w = xb[64 * j]; v[j] = (f32x4){bflo(w.x), bfhi(w.x), bflo(w.y), bfhi(w.y)}; s += (v[j].x * v[j].x + v[j].y * v[j].y) + (v[j].z * v[j].z + v[j].w * v[j].w); }
;         const float rs = rsqrtf(wave_sum(s, lane) * (1.f / DM) + EPS); const f32x4* gr = (const f32x4*)gf + lane;
; #pragma unroll
;         for (int j = 0; j < 8; ++j) { const f32x4 gv = gr[64 * j]; xr[64 * j] = (f32x4){v[j].x * rs * gv.x, v[j].y * rs * gv.y, v[j].z * rs * gv.z, v[j].w * rs * gv.w}; } } }
	v_add_f32_e32 v25, v25, v60
	s_nop 1
	v_mov_b32_dpp v60, v25 quad_perm:[2,3,0,1] row_mask:0xf bank_mask:0xf
	s_waitcnt lgkmcnt(0)
	v_add_f32_e32 v25, v25, v60
	s_nop 1
	v_mov_b32_dpp v60, v25 row_half_mirror row_mask:0xf bank_mask:0xf
	s_waitcnt lgkmcnt(0)
	v_add_f32_e32 v25, v25, v60
	s_nop 1
	v_mov_b32_dpp v60, v25 row_mirror row_mask:0xf bank_mask:0xf
	s_waitcnt lgkmcnt(0)
	v_add_f32_e32 v25, v25, v60
	v_mov_b32_e32 v60, v25
	s_nop 1
	v_permlane16_swap_b32_e32 v60, v25
	s_waitcnt lgkmcnt(0)
	v_add_f32_e32 v25, v25, v60
	v_mov_b32_e32 v60, v25
	s_nop 1
	v_permlane32_swap_b32_e32 v60, v25
	s_waitcnt lgkmcnt(0)
	v_add_f32_e32 v25, v25, v60
	v_fmamk_f32 v25, v25, 0x3a000000, v24
	v_mul_f32_e32 v60, 0x4b800000, v25
	v_cmp_gt_f32_e32 vcc, s1, v25
	s_nop 1
	v_cndmask_b32_e32 v25, v25, v60, vcc
	v_rsq_f32_e32 v25, v25
	s_nop 0
	v_mul_f32_e32 v60, 0x45800000, v25
	v_cndmask_b32_e32 v60, v25, v60, vcc
	v_pk_mul_f32 v[44:45], v[60:61], v[44:45] op_sel_hi:[0,1]
	v_pk_mul_f32 v[26:27], v[60:61], v[26:27] op_sel_hi:[0,1]
	s_waitcnt vmcnt(0)
	v_pk_mul_f32 v[0:1], v[0:1], v[44:45]
	v_pk_mul_f32 v[2:3], v[2:3], v[26:27]
	global_store_dwordx4 v[42:43], v[0:3], off offset:-3072
	global_load_dwordx4 v[0:3], v[4:5], off offset:1024
	v_pk_mul_f32 v[26:27], v[60:61], v[46:47] op_sel_hi:[0,1]
	v_pk_mul_f32 v[28:29], v[60:61], v[28:29] op_sel_hi:[0,1]
	s_waitcnt vmcnt(0)
	v_pk_mul_f32 v[0:1], v[0:1], v[26:27]
	v_pk_mul_f32 v[2:3], v[2:3], v[28:29]
	global_store_dwordx4 v[42:43], v[0:3], off offset:-2048
	global_load_dwordx4 v[0:3], v[4:5], off offset:2048
	v_pk_mul_f32 v[26:27], v[60:61], v[48:49] op_sel_hi:[0,1]
	v_pk_mul_f32 v[28:29], v[60:61], v[30:31] op_sel_hi:[0,1]
	s_waitcnt vmcnt(0)
	v_pk_mul_f32 v[0:1], v[0:1], v[26:27]
	v_pk_mul_f32 v[2:3], v[2:3], v[28:29]
	global_store_dwordx4 v[42:43], v[0:3], off offset:-1024
	global_load_dwordx4 v[0:3], v[4:5], off offset:3072
	v_pk_mul_f32 v[26:27], v[60:61], v[32:33] op_sel_hi:[0,1]
	v_pk_mul_f32 v[28:29], v[60:61], v[50:51] op_sel_hi:[0,1]
	s_waitcnt vmcnt(0)
	v_pk_mul_f32 v[0:1], v[0:1], v[28:29]
	v_pk_mul_f32 v[2:3], v[2:3], v[26:27]
	global_store_dwordx4 v[14:15], v[0:3], off offset:-4096
	global_load_dwordx4 v[0:3], v[6:7], off
	v_pk_mul_f32 v[26:27], v[60:61], v[34:35] op_sel_hi:[0,1]
	v_pk_mul_f32 v[28:29], v[60:61], v[52:53] op_sel_hi:[0,1]
	s_waitcnt vmcnt(0)
	v_pk_mul_f32 v[0:1], v[0:1], v[28:29]
	v_pk_mul_f32 v[2:3], v[2:3], v[26:27]
	global_store_dwordx4 v[14:15], v[0:3], off offset:-3072
	global_load_dwordx4 v[0:3], v[8:9], off
	v_pk_mul_f32 v[26:27], v[60:61], v[54:55] op_sel_hi:[0,1]
	v_pk_mul_f32 v[28:29], v[60:61], v[36:37] op_sel_hi:[0,1]
	s_waitcnt vmcnt(0)
	v_pk_mul_f32 v[0:1], v[0:1], v[26:27]
	v_pk_mul_f32 v[2:3], v[2:3], v[28:29]
	global_store_dwordx4 v[14:15], v[0:3], off offset:-2048
	global_load_dwordx4 v[0:3], v[10:11], off
	v_pk_mul_f32 v[26:27], v[60:61], v[38:39] op_sel_hi:[0,1]
	v_pk_mul_f32 v[28:29], v[60:61], v[56:57] op_sel_hi:[0,1]
	s_waitcnt vmcnt(0)
	v_pk_mul_f32 v[0:1], v[0:1], v[28:29]
	v_pk_mul_f32 v[2:3], v[2:3], v[26:27]
	global_store_dwordx4 v[14:15], v[0:3], off offset:-1024
	global_load_dwordx4 v[0:3], v[12:13], off
	v_pk_mul_f32 v[26:27], v[60:61], v[40:41] op_sel_hi:[0,1]
	v_pk_mul_f32 v[28:29], v[60:61], v[58:59] op_sel_hi:[0,1]
	s_waitcnt vmcnt(0)
	v_pk_mul_f32 v[0:1], v[0:1], v[28:29]
	v_pk_mul_f32 v[2:3], v[2:3], v[26:27]
	global_store_dwordx4 v[14:15], v[0:3], off
	v_lshl_add_u64 v[14:15], v[14:15], 0, s[4:5]
	s_cbranch_scc1 .LBB0_1808
